# seam after FFN1-down split: arrive on the grid barrier, wait only for the panel's four owners; wave 0 checks the global round before the in-projection's first epilogue stores (write-after-read guard)
# speedup vs baseline: 1.0133x; 1.0084x over previous
; #define LAS __attribute__((address_space(3)))
; __global__ void __launch_bounds__(NT, 2) hymba_fwd(Args args) {
;     extern __shared__ __attribute__((aligned(16))) unsigned char lds_raw[];
;     LAS unsigned char* lds = (LAS unsigned char*)lds_raw;
;     const int tid = threadIdx.x, lane = tid & 63, wave = __builtin_amdgcn_readfirstlane(tid >> 6);
;     const int G = gridDim.x, bx = blockIdx.x;
;     const int vcu = (G % 8 == 0) ? (bx % 8) * (G / 8) + bx / 8 : bx;
;     const int gw = vcu * NWAVES + wave, NGW = G * NWAVES;
;     unsigned char* ws = args.ws;
;     float* ssq = (float*)(ws + WS_SSQ);
;     const int lo = args.ph_lo, hi = args.ph_hi;
_Z9hymba_fwd4Args:
	s_mov_b32 s100, 0
	s_mov_b32 s101, 0
	s_load_dword s3, s[0:1], 0xc0
	s_add_u32 s4, s0, 0xc0
	s_addc_u32 s5, s1, 0
	v_and_b32_e32 v209, 0x3ff, v0
	v_writelane_b32 v248, s4, 0
	v_readfirstlane_b32 s56, v209
	s_mov_b32 s60, s2
	v_writelane_b32 v248, s5, 1
	s_waitcnt lgkmcnt(0)
	s_and_b32 s4, s3, 7
	s_cmp_lg_u32 s4, 0
	s_cbranch_scc0 .LBB0_77
	s_load_dwordx4 s[48:51], s[0:1], 0xb0
	s_waitcnt lgkmcnt(0)
	s_cmp_gt_i32 s50, -1
	s_cbranch_scc0 .LBB0_78

; __device__ __forceinline__ unsigned xb_ld(unsigned* p)              { return __hip_atomic_load(p, __ATOMIC_RELAXED, __HIP_MEMORY_SCOPE_AGENT); }
; __device__ __forceinline__ unsigned xb_add(unsigned* p, unsigned v) { return __hip_atomic_fetch_add(p, v, __ATOMIC_RELAXED, __HIP_MEMORY_SCOPE_AGENT); }
; #define XB_SPIN(cond, bar) do { unsigned _sp = 0; while (cond) { __builtin_amdgcn_s_sleep(1); \
;     if ((++_sp & 255u) == 0u) { if (xb_ld(&(bar)[XB_TMO])) break; if (_sp > XB_SPIN_CAP) { atomicAdd(&(bar)[XB_TMO], 1u); break; } } } } while (0)
; __device__ __forceinline__ void xcd_barrier(const XcdBarrier& b) {
;     asm volatile("s_waitcnt vmcnt(0)" ::: "memory");
;     __syncthreads();
;     if (threadIdx.x == 0) {
;         unsigned* bar = b.bar;
;         __builtin_amdgcn_s_waitcnt(0);
;         unsigned nloc = b.st[0], nx = b.st[1];
;         if (nloc == 0u) { xcd_barrier_complete(bar, b.x, nloc, nx); b.st[0] = nloc; b.st[1] = nx; }
;         const unsigned old = xb_add(&bar[XB_XSUB(b.x)], 1u);
;         const unsigned gen = old / nloc;
;         if (old + 1u == (gen + 1u) * nloc) {
;             __builtin_amdgcn_fence(__ATOMIC_RELEASE, "agent");
;             asm volatile("s_waitcnt vmcnt(0)" ::: "memory");
;             const unsigned og = xb_add(&bar[XB_TOP], 1u);
;             const unsigned tg = og / nx;
;             if (og + 1u == (tg + 1u) * nx) xb_add(&bar[XB_TOPGEN], 1u);
;             else XB_SPIN(xb_ld(&bar[XB_TOPGEN]) == tg, bar);
;             __builtin_amdgcn_fence(__ATOMIC_ACQUIRE, "agent");
;             xb_add(&bar[XB_XGEN(b.x)], 1u);
.LBB0_392:
	s_cmp_gt_i32 s51, 3
	s_cselect_b64 s[4:5], -1, 0
	s_and_b64 s[6:7], s[10:11], s[4:5]
	s_andn2_b64 vcc, exec, s[6:7]
	s_cbranch_vccnz .LBB0_446
	v_mov_b32_e32 v1, 0x23fc8
	ds_read_b32 v2, v1
	s_waitcnt lgkmcnt(0)
	v_readfirstlane_b32 s14, v2
	s_cmp_lg_u32 s14, 1
	s_cbranch_scc1 .Lgb2_full
	s_waitcnt vmcnt(0)
	s_barrier
	s_cmp_eq_u64 s[44:45], 0
	s_cbranch_scc1 .Lgb2_gend
	s_mov_b64 s[8:9], exec
	s_mov_b64 exec, s[44:45]
	s_lshl_b32 s10, s33, 8
	s_add_u32 s12, s46, s10
	s_addc_u32 s13, s47, 0
	v_mov_b32_e32 v1, 0x23fc0
	ds_read2_b32 v[2:3], v1 offset1:1
	v_mov_b32_e32 v4, 0x1400
	v_mov_b32_e32 v1, 1
	global_atomic_add v4, v4, v1, s[12:13] sc0
	s_add_i32 s17, s100, 1
	s_waitcnt vmcnt(0) lgkmcnt(0)
	v_readfirstlane_b32 s14, v4
	v_readfirstlane_b32 s15, v2
	v_readfirstlane_b32 s16, v3
	s_mul_i32 s18, s17, s15
	s_mul_i32 s101, s17, s16
	s_add_i32 s14, s14, 1
	s_cmp_lg_u32 s14, s18
	s_cbranch_scc1 .Lgb2_gnolead
	v_mov_b32_e32 v0, 0x10000
	global_atomic_add v0, v1, s[46:47]
	global_atomic_add v0, v1, s[46:47] offset:256
	global_atomic_add v0, v1, s[46:47] offset:512
	global_atomic_add v0, v1, s[46:47] offset:768
	global_atomic_add v0, v1, s[46:47] offset:1024
	global_atomic_add v0, v1, s[46:47] offset:1280
	global_atomic_add v0, v1, s[46:47] offset:1536
	global_atomic_add v0, v1, s[46:47] offset:1792
	global_atomic_add v0, v1, s[46:47] offset:2048
	global_atomic_add v0, v1, s[46:47] offset:2304
	global_atomic_add v0, v1, s[46:47] offset:2560
	global_atomic_add v0, v1, s[46:47] offset:2816
	global_atomic_add v0, v1, s[46:47] offset:3072
	global_atomic_add v0, v1, s[46:47] offset:3328
	global_atomic_add v0, v1, s[46:47] offset:3584
	global_atomic_add v0, v1, s[46:47] offset:3840

; __device__ __forceinline__ unsigned xb_ld(unsigned* p)              { return __hip_atomic_load(p, __ATOMIC_RELAXED, __HIP_MEMORY_SCOPE_AGENT); }
; __device__ __forceinline__ unsigned xb_add(unsigned* p, unsigned v) { return __hip_atomic_fetch_add(p, v, __ATOMIC_RELAXED, __HIP_MEMORY_SCOPE_AGENT); }
; #define XB_SPIN(cond, bar) do { unsigned _sp = 0; while (cond) { __builtin_amdgcn_s_sleep(1); \
;     if ((++_sp & 255u) == 0u) { if (xb_ld(&(bar)[XB_TMO])) break; if (_sp > XB_SPIN_CAP) { atomicAdd(&(bar)[XB_TMO], 1u); break; } } } } while (0)
; __device__ __forceinline__ void xcd_barrier(const XcdBarrier& b) {
;     ...
;             __builtin_amdgcn_fence(__ATOMIC_ACQUIRE, "agent");
;             xb_add(&bar[XB_XGEN(b.x)], 1u);
;             asm volatile("s_waitcnt vmcnt(0)" ::: "memory");
;         } else {
;             XB_SPIN(xb_ld(&bar[XB_XGEN(b.x)]) == gen, bar);
;             __builtin_amdgcn_fence(__ATOMIC_ACQUIRE, "agent");
;             asm volatile("s_waitcnt vmcnt(0)" ::: "memory");
;         }
;     }
;     __syncthreads();
.Lgb2_gacq:
	buffer_inv sc1
	s_waitcnt vmcnt(0)
	s_mov_b64 exec, s[8:9]
.Lgb2_gend:
	s_barrier
	s_add_i32 s100, s100, 1
	s_branch .Lgb2_after
.Lgb2_full:
	s_cmp_eq_u64 s[44:45], 0
	s_cbranch_scc1 .Lgb2_drain
	s_mov_b64 s[8:9], exec
	s_mov_b64 exec, s[44:45]
	s_lshl_b32 s10, s33, 8
	s_add_u32 s12, s46, s10
	s_addc_u32 s13, s47, 0
	v_mov_b32_e32 v1, 0x23fc0
	ds_read2_b32 v[2:3], v1 offset1:1
	v_mov_b32_e32 v0, 0x10000
	global_load_dword v5, v0, s[12:13] sc1
	s_mov_b64 exec, s[8:9]

;     __host__ __device__ bool next(int i, Unit& u) const {
;         const long L = (long)i * G + c; if (L >= nwg) return false;
;         int wgid = (int)L; { const int q = nwg / NXCD, r = nwg % NXCD, xcd = wgid % NXCD, off = wgid / NXCD; wgid = (xcd < r ? xcd * (q + 1) : r * (q + 1) + (xcd - r) * q) + off; }
;         const int nig = WGM * nN, gid = wgid / nig, fm = gid * WGM, gsz = (nM - fm) < WGM ? (nM - fm) : WGM;
;         u.pm = fm + ((wgid % nig) % gsz); u.pn = (wgid % nig) / gsz; return true;
; __global__ void __launch_bounds__(NT, 2) hymba_fwd(Args args) {
;     ...
;     if (IN(3)) _Pragma("unroll") for (int rep = 0; rep < NREP(3); ++rep) {
;         pg8::Gemm g{XB, (const bf16*)(ws + WS_WIN), M, 2048, D}; pg8::StaticOrder S; S.init(M, 2048, G, bx);
;         pg8::EpiWin E{(bf16*)(ws + WS_QS), (bf16*)(ws + WS_VV), (bf16*)(ws + WS_GS), (bf16*)(ws + WS_BC), (bf16*)(ws + WS_CU), (_Float16*)(ws + WS_LF), ssq + M, args.in[I_LB], 0};
;         pg8::gemm_phase<pg8::EpiWin, pg8::StaticOrder, true, true>(lds, g, S, E);
.Lgb2_after:
.LBB0_446:
	s_cmp_lt_i32 s50, 4
	s_cselect_b64 s[6:7], -1, 0
	s_and_b64 s[10:11], s[6:7], s[4:5]
	s_andn2_b64 vcc, exec, s[10:11]
	s_cbranch_vccnz .LBB0_518
	s_cmpk_lt_i32 s2, 0x200
	s_cselect_b64 s[4:5], -1, 0
	s_cmpk_gt_i32 s2, 0x1ff
	v_readfirstlane_b32 s36, v209
	s_cbranch_scc1 .LBB0_449
	s_ashr_i32 s6, s2, 31
	s_lshr_b32 s6, s6, 29
	s_add_i32 s6, s2, s6
	s_and_b32 s7, s6, -8
	s_sub_i32 s7, s2, s7
	s_lshl_b32 s9, s7, 6
	s_ashr_i32 s6, s6, 3
	s_mul_i32 s8, s7, 0x41
	s_cmp_lt_i32 s7, 0
	s_cselect_b32 s7, s8, s9
	s_add_i32 s6, s7, s6
	s_ashr_i32 s7, s6, 31
	s_lshr_b32 s7, s7, 26
	s_add_i32 s7, s6, s7
	s_ashr_i32 s8, s7, 6
	s_andn2_b32 s7, s7, 63
	s_sub_i32 s6, s6, s7
	s_bfe_i32 s7, s6, 0x80000
	s_bfe_u32 s7, s7, 0x3000c
	s_add_i32 s7, s6, s7
	s_bfe_i32 s9, s7, 0x80000
	s_and_b32 s7, s7, 0xf8
	s_sub_i32 s6, s6, s7
	s_lshl_b32 s8, s8, 3
	s_sext_i32_i16 s9, s9
	s_sext_i32_i8 s6, s6
	s_add_i32 s6, s8, s6
	s_ashr_i32 s14, s9, 3

; #define PG8_STAGE(bufoff, gbase, voff) do { _Pragma("unroll") for (int _i = 0; _i < 2; ++_i) \
;         __builtin_amdgcn_global_load_lds((const unsigned*)((const char*)(gbase) + (voff)[_i]), (PG8_LAS unsigned*)(lds + (bufoff) + ldsw + _i * 8192), 16, 0, 0); } while (0)
; #define PG8_LDA(dst, b, h) do { _Pragma("unroll") for (int m = 0; m < 4; ++m) _Pragma("unroll") for (int k = 0; k < 2; ++k) dst[m][k] = *(const PG8_LAS bf16x8*)(lds + PG8_SA(b, h) + aoff + m * 2048 + k * 1024); } while (0)
; #define PG8_LDB(dst, b, h) do { _Pragma("unroll") for (int n = 0; n < 2; ++n) _Pragma("unroll") for (int k = 0; k < 2; ++k) dst[n][k] = *(const PG8_LAS bf16x8*)(lds + PG8_SB(b, h) + boff + n * 2048 + k * 1024); } while (0)
; #define PG8_MMA(ai, bj, At, Bt) do { __builtin_amdgcn_s_setprio(1); _Pragma("unroll") for (int m = 0; m < 4; ++m) _Pragma("unroll") for (int n = 0; n < 2; ++n) _Pragma("unroll") for (int k = 0; k < 2; ++k) \
;         acc[ai][bj][m][n] = __builtin_amdgcn_mfma_f32_16x16x32_bf16(Bt[n][k], At[m][k], acc[ai][bj][m][n], 0, 0, 0); __builtin_amdgcn_s_setprio(0); } while (0)
; #define PG8_BAR __builtin_amdgcn_s_barrier()
; template <class Epi, class Sched, bool ALIGN_EPI = false, bool SP2 = false>
; __device__ __forceinline__ void gemm_phase(PG8_LAS unsigned char* lds, const Gemm g, const Sched& S, const Epi& E) {
;     ...
;             if constexpr (SP2) {
;             PG8_LDB(B0, 0, 0); PG8_LDB(B1, 0, 1); PG8_SCHED; PG8_LDA(At, 0, 0); PG8_STAGE(PG8_SA(1, 1), a1 + hstep, voffA);
;             PG8_WAIT_V(8); PG8_WAIT_L(0); PG8_BAR; PG8_MMA(0, 0, At, B0); PG8_MMA(0, 1, At, B1); PG8_BAR; PG8_SCHED;
;             PG8_LDA(At, 0, 1); PG8_STAGE(PG8_SB(0, 0), b2, voffB); PG8_STAGE(PG8_SB(0, 1), b2 + hstep, voffB); PG8_STAGE(PG8_SA(0, 0), a2, voffA);
;             PG8_WAIT_V(8); PG8_WAIT_L(0); PG8_BAR; PG8_MMA(1, 0, At, B0); PG8_MMA(1, 1, At, B1); PG8_BAR; PG8_SCHED;
;             PG8_LDB(B0, 1, 0); PG8_LDB(B1, 1, 1); PG8_SCHED; PG8_LDA(At, 1, 0); PG8_STAGE(PG8_SA(0, 1), a2 + hstep, voffA);
;             PG8_WAIT_V(8); PG8_WAIT_L(0); PG8_BAR; PG8_MMA(0, 0, At, B0); PG8_MMA(0, 1, At, B1); PG8_BAR; PG8_SCHED;
;             PG8_LDA(At, 1, 1); PG8_STAGE(PG8_SB(1, 0), b3, voffB); PG8_STAGE(PG8_SB(1, 1), b3 + hstep, voffB); PG8_STAGE(PG8_SA(1, 0), a3, voffA);
;             PG8_WAIT_V(8); PG8_WAIT_L(0); PG8_BAR; PG8_MMA(1, 0, At, B0); PG8_MMA(1, 1, At, B1); PG8_BAR; PG8_SCHED;
.LBB0_462:
	ds_read_b128 v[148:151], v167
	ds_read_b128 v[152:155], v167 offset:1024
	ds_read_b128 v[156:159], v167 offset:2048
	ds_read_b128 v[160:163], v167 offset:3072
	ds_read_b128 v[172:175], v168
	ds_read_b128 v[176:179], v168 offset:1024
	ds_read_b128 v[180:183], v168 offset:2048
	ds_read_b128 v[184:187], v168 offset:3072
	s_add_u32 s52, s8, 0xfffc0080
	s_addc_u32 s53, s9, -1
	s_cmp_eq_u32 vcc_lo, 12
	s_cselect_b32 s75, s7, s53
	s_cselect_b32 s74, s67, s52
	s_cselect_b32 s73, s65, s97
	s_cselect_b32 s72, s95, s96
	v_lshl_add_u64 v[164:165], s[8:9], 0, v[140:141]
	s_add_i32 m0, s76, 0xc000
	ds_read_b128 v[188:191], v169
	ds_read_b128 v[192:195], v169 offset:1024
	ds_read_b128 v[196:199], v169 offset:2048
	ds_read_b128 v[200:203], v169 offset:3072
	ds_read_b128 v[204:207], v169 offset:4096
	ds_read_b128 v[210:213], v169 offset:5120
	ds_read_b128 v[214:217], v169 offset:6144
	ds_read_b128 v[218:221], v169 offset:7168
	global_load_lds_dwordx4 v[164:165], off
	v_lshl_add_u64 v[164:165], s[8:9], 0, v[142:143]
	s_add_i32 m0, s76, 0xe000
	s_nop 0
	global_load_lds_dwordx4 v[164:165], off
	s_waitcnt vmcnt(8)
	s_waitcnt lgkmcnt(0)
	s_barrier
	s_setprio 1
	s_waitcnt lgkmcnt(0)
	v_mfma_f32_16x16x32_bf16 v[124:127], v[148:151], v[188:191], v[124:127]
	v_mfma_f32_16x16x32_bf16 v[120:123], v[156:159], v[188:191], v[120:123]
	v_mfma_f32_16x16x32_bf16 v[108:111], v[148:151], v[196:199], v[108:111]
	v_mfma_f32_16x16x32_bf16 v[104:107], v[156:159], v[196:199], v[104:107]
	v_mfma_f32_16x16x32_bf16 v[92:95], v[148:151], v[204:207], v[92:95]
	v_mfma_f32_16x16x32_bf16 v[88:91], v[156:159], v[204:207], v[88:91]
	v_mfma_f32_16x16x32_bf16 v[76:79], v[148:151], v[214:217], v[76:79]
	v_mfma_f32_16x16x32_bf16 v[72:75], v[156:159], v[214:217], v[72:75]
	v_mfma_f32_16x16x32_bf16 v[124:127], v[152:155], v[192:195], v[124:127]
	v_mfma_f32_16x16x32_bf16 v[120:123], v[160:163], v[192:195], v[120:123]
	v_mfma_f32_16x16x32_bf16 v[108:111], v[152:155], v[200:203], v[108:111]
	v_mfma_f32_16x16x32_bf16 v[104:107], v[160:163], v[200:203], v[104:107]
	v_mfma_f32_16x16x32_bf16 v[92:95], v[152:155], v[210:213], v[92:95]
	v_mfma_f32_16x16x32_bf16 v[88:91], v[160:163], v[210:213], v[88:91]
	v_mfma_f32_16x16x32_bf16 v[76:79], v[152:155], v[218:221], v[76:79]
	v_mfma_f32_16x16x32_bf16 v[72:75], v[160:163], v[218:221], v[72:75]
	s_setprio 0
	s_setprio 1
	v_mfma_f32_16x16x32_bf16 v[116:119], v[172:175], v[188:191], v[116:119]
	v_mfma_f32_16x16x32_bf16 v[112:115], v[180:183], v[188:191], v[112:115]
	v_mfma_f32_16x16x32_bf16 v[100:103], v[172:175], v[196:199], v[100:103]
	v_mfma_f32_16x16x32_bf16 v[96:99], v[180:183], v[196:199], v[96:99]
	v_mfma_f32_16x16x32_bf16 v[84:87], v[172:175], v[204:207], v[84:87]
	v_mfma_f32_16x16x32_bf16 v[80:83], v[180:183], v[204:207], v[80:83]
	v_mfma_f32_16x16x32_bf16 v[68:71], v[172:175], v[214:217], v[68:71]
	v_mfma_f32_16x16x32_bf16 v[64:67], v[180:183], v[214:217], v[64:67]
	v_mfma_f32_16x16x32_bf16 v[116:119], v[176:179], v[192:195], v[116:119]
	v_mfma_f32_16x16x32_bf16 v[112:115], v[184:187], v[192:195], v[112:115]
	v_mfma_f32_16x16x32_bf16 v[100:103], v[176:179], v[200:203], v[100:103]
	v_mfma_f32_16x16x32_bf16 v[96:99], v[184:187], v[200:203], v[96:99]
	v_mfma_f32_16x16x32_bf16 v[84:87], v[176:179], v[210:213], v[84:87]
	v_mfma_f32_16x16x32_bf16 v[80:83], v[184:187], v[210:213], v[80:83]
	v_mfma_f32_16x16x32_bf16 v[68:71], v[176:179], v[218:221], v[68:71]
	v_mfma_f32_16x16x32_bf16 v[64:67], v[184:187], v[218:221], v[64:67]
	s_setprio 0
	s_barrier
	s_add_i32 s52, s85, s61
	v_lshl_add_u64 v[164:165], s[72:73], 0, v[130:131]
	s_mov_b32 m0, s52
	ds_read_b128 v[188:191], v169 offset:16384
	ds_read_b128 v[192:195], v169 offset:17408
	ds_read_b128 v[196:199], v169 offset:18432
	ds_read_b128 v[200:203], v169 offset:19456
	ds_read_b128 v[204:207], v169 offset:20480
	ds_read_b128 v[210:213], v169 offset:21504
	ds_read_b128 v[214:217], v169 offset:22528
	ds_read_b128 v[218:221], v169 offset:23552
	global_load_lds_dwordx4 v[164:165], off
	s_add_i32 m0, s52, 0x2000
	s_add_u32 s52, s72, 0x40000
	v_lshl_add_u64 v[222:223], s[72:73], 0, v[134:135]
	s_addc_u32 s53, s73, 0
	s_add_i32 s78, s86, s61
	global_load_lds_dwordx4 v[222:223], off
	v_lshl_add_u64 v[224:225], s[52:53], 0, v[130:131]
	s_mov_b32 m0, s78
	v_lshl_add_u64 v[226:227], s[74:75], 0, v[132:133]
	global_load_lds_dwordx4 v[224:225], off
	v_lshl_add_u64 v[224:225], s[52:53], 0, v[134:135]
	s_add_i32 m0, s78, 0x2000
	s_nop 0
	global_load_lds_dwordx4 v[224:225], off
	v_lshl_add_u64 v[224:225], s[74:75], 0, v[128:129]
	s_mov_b32 m0, s76
	s_nop 0
	global_load_lds_dwordx4 v[224:225], off
	s_mov_b32 m0, s77
	s_nop 0
	global_load_lds_dwordx4 v[226:227], off
	s_waitcnt vmcnt(8)
	s_waitcnt lgkmcnt(0)
	s_barrier
; #define PG8_STAGE(bufoff, gbase, voff) do { _Pragma("unroll") for (int _i = 0; _i < 2; ++_i) \
;         __builtin_amdgcn_global_load_lds((const unsigned*)((const char*)(gbase) + (voff)[_i]), (PG8_LAS unsigned*)(lds + (bufoff) + ldsw + _i * 8192), 16, 0, 0); } while (0)
; #define PG8_LDA(dst, b, h) do { _Pragma("unroll") for (int m = 0; m < 4; ++m) _Pragma("unroll") for (int k = 0; k < 2; ++k) dst[m][k] = *(const PG8_LAS bf16x8*)(lds + PG8_SA(b, h) + aoff + m * 2048 + k * 1024); } while (0)
; #define PG8_LDB(dst, b, h) do { _Pragma("unroll") for (int n = 0; n < 2; ++n) _Pragma("unroll") for (int k = 0; k < 2; ++k) dst[n][k] = *(const PG8_LAS bf16x8*)(lds + PG8_SB(b, h) + boff + n * 2048 + k * 1024); } while (0)
; #define PG8_MMA(ai, bj, At, Bt) do { __builtin_amdgcn_s_setprio(1); _Pragma("unroll") for (int m = 0; m < 4; ++m) _Pragma("unroll") for (int n = 0; n < 2; ++n) _Pragma("unroll") for (int k = 0; k < 2; ++k) \
;         acc[ai][bj][m][n] = __builtin_amdgcn_mfma_f32_16x16x32_bf16(Bt[n][k], At[m][k], acc[ai][bj][m][n], 0, 0, 0); __builtin_amdgcn_s_setprio(0); } while (0)
; #define PG8_WAIT_V(n) asm volatile("s_waitcnt vmcnt(" #n ")" ::: "memory")
; #define PG8_WAIT_L(n) asm volatile("s_waitcnt lgkmcnt(" #n ")" ::: "memory")
; template <class Epi, class Sched, bool ALIGN_EPI = false, bool SP2 = false>
; __device__ __forceinline__ void gemm_phase(PG8_LAS unsigned char* lds, const Gemm g, const Sched& S, const Epi& E) {
;     ...
;             PG8_LDB(B0, 0, 0); PG8_LDB(B1, 0, 1); PG8_SCHED; PG8_LDA(At, 0, 0); PG8_STAGE(PG8_SA(1, 1), a1 + hstep, voffA);
;             PG8_WAIT_V(8); PG8_WAIT_L(0); PG8_BAR; PG8_MMA(0, 0, At, B0); PG8_MMA(0, 1, At, B1); PG8_BAR; PG8_SCHED;
;             PG8_LDA(At, 0, 1); PG8_STAGE(PG8_SB(0, 0), b2, voffB); PG8_STAGE(PG8_SB(0, 1), b2 + hstep, voffB); PG8_STAGE(PG8_SA(0, 0), a2, voffA);
;             PG8_WAIT_V(8); PG8_WAIT_L(0); PG8_BAR; PG8_MMA(1, 0, At, B0); PG8_MMA(1, 1, At, B1); PG8_BAR; PG8_SCHED;
;             PG8_LDB(B0, 1, 0); PG8_LDB(B1, 1, 1); PG8_SCHED; PG8_LDA(At, 1, 0); PG8_STAGE(PG8_SA(0, 1), a2 + hstep, voffA);
;             PG8_WAIT_V(8); PG8_WAIT_L(0); PG8_BAR; PG8_MMA(0, 0, At, B0); PG8_MMA(0, 1, At, B1); PG8_BAR; PG8_SCHED;
;             PG8_LDA(At, 1, 1); PG8_STAGE(PG8_SB(1, 0), b3, voffB); PG8_STAGE(PG8_SB(1, 1), b3 + hstep, voffB); PG8_STAGE(PG8_SA(1, 0), a3, voffA);
	s_setprio 1
	s_waitcnt lgkmcnt(0)
	v_mfma_f32_16x16x32_bf16 v[60:63], v[148:151], v[188:191], v[60:63]
	v_mfma_f32_16x16x32_bf16 v[56:59], v[156:159], v[188:191], v[56:59]
	v_mfma_f32_16x16x32_bf16 v[44:47], v[148:151], v[196:199], v[44:47]
	v_mfma_f32_16x16x32_bf16 v[40:43], v[156:159], v[196:199], v[40:43]
	v_mfma_f32_16x16x32_bf16 v[28:31], v[148:151], v[204:207], v[28:31]
	v_mfma_f32_16x16x32_bf16 v[24:27], v[156:159], v[204:207], v[24:27]
	v_mfma_f32_16x16x32_bf16 v[12:15], v[148:151], v[214:217], v[12:15]
	v_mfma_f32_16x16x32_bf16 v[8:11], v[156:159], v[214:217], v[8:11]
	v_mfma_f32_16x16x32_bf16 v[60:63], v[152:155], v[192:195], v[60:63]
	v_mfma_f32_16x16x32_bf16 v[56:59], v[160:163], v[192:195], v[56:59]
	v_mfma_f32_16x16x32_bf16 v[44:47], v[152:155], v[200:203], v[44:47]
	v_mfma_f32_16x16x32_bf16 v[40:43], v[160:163], v[200:203], v[40:43]
	v_mfma_f32_16x16x32_bf16 v[28:31], v[152:155], v[210:213], v[28:31]
	v_mfma_f32_16x16x32_bf16 v[24:27], v[160:163], v[210:213], v[24:27]
	v_mfma_f32_16x16x32_bf16 v[12:15], v[152:155], v[218:221], v[12:15]
	v_mfma_f32_16x16x32_bf16 v[8:11], v[160:163], v[218:221], v[8:11]
	s_setprio 0
	s_setprio 1
	v_mfma_f32_16x16x32_bf16 v[52:55], v[172:175], v[188:191], v[52:55]
	v_mfma_f32_16x16x32_bf16 v[48:51], v[180:183], v[188:191], v[48:51]
	v_mfma_f32_16x16x32_bf16 v[36:39], v[172:175], v[196:199], v[36:39]
	v_mfma_f32_16x16x32_bf16 v[32:35], v[180:183], v[196:199], v[32:35]
	v_mfma_f32_16x16x32_bf16 v[20:23], v[172:175], v[204:207], v[20:23]
	v_mfma_f32_16x16x32_bf16 v[16:19], v[180:183], v[204:207], v[16:19]
	v_mfma_f32_16x16x32_bf16 v[4:7], v[172:175], v[214:217], v[4:7]
	v_mfma_f32_16x16x32_bf16 v[0:3], v[180:183], v[214:217], v[0:3]
	v_mfma_f32_16x16x32_bf16 v[52:55], v[176:179], v[192:195], v[52:55]
	v_mfma_f32_16x16x32_bf16 v[48:51], v[184:187], v[192:195], v[48:51]
	v_mfma_f32_16x16x32_bf16 v[36:39], v[176:179], v[200:203], v[36:39]
	v_mfma_f32_16x16x32_bf16 v[32:35], v[184:187], v[200:203], v[32:35]
	v_mfma_f32_16x16x32_bf16 v[20:23], v[176:179], v[210:213], v[20:23]
	v_mfma_f32_16x16x32_bf16 v[16:19], v[184:187], v[210:213], v[16:19]
	v_mfma_f32_16x16x32_bf16 v[4:7], v[176:179], v[218:221], v[4:7]
	v_mfma_f32_16x16x32_bf16 v[0:3], v[184:187], v[218:221], v[0:3]
	s_setprio 0
	s_barrier
	s_add_i32 s78, 0, 0x18000
	v_add_u32_e32 v136, s78, v166
	s_add_i32 vcc_hi, 0, 0x1c000
	ds_read_b128 v[148:151], v136
	ds_read_b128 v[152:155], v136 offset:1024
	ds_read_b128 v[156:159], v136 offset:2048
	ds_read_b128 v[160:163], v136 offset:3072
	v_add_u32_e32 v136, vcc_hi, v166
	ds_read_b128 v[172:175], v136
	ds_read_b128 v[176:179], v136 offset:1024
	ds_read_b128 v[180:183], v136 offset:2048
	ds_read_b128 v[184:187], v136 offset:3072
	s_add_u32 s52, s74, 0x40000
	s_addc_u32 s53, s75, 0
	s_mov_b32 m0, s79
	v_lshl_add_u64 v[228:229], s[52:53], 0, v[128:129]
	ds_read_b128 v[188:191], v169 offset:32768
	ds_read_b128 v[192:195], v169 offset:33792
	ds_read_b128 v[196:199], v169 offset:34816
	ds_read_b128 v[200:203], v169 offset:35840
	ds_read_b128 v[204:207], v169 offset:36864
	ds_read_b128 v[210:213], v169 offset:37888
	ds_read_b128 v[214:217], v169 offset:38912
	ds_read_b128 v[218:221], v169 offset:39936
	global_load_lds_dwordx4 v[228:229], off
	v_lshl_add_u64 v[228:229], s[52:53], 0, v[132:133]
	s_mov_b32 m0, s80
	s_nop 0
	global_load_lds_dwordx4 v[228:229], off
	s_waitcnt vmcnt(8)
	s_waitcnt lgkmcnt(0)
	s_barrier
	s_setprio 1
	s_waitcnt lgkmcnt(0)
	v_mfma_f32_16x16x32_bf16 v[124:127], v[148:151], v[188:191], v[124:127]
	v_mfma_f32_16x16x32_bf16 v[120:123], v[156:159], v[188:191], v[120:123]
	v_mfma_f32_16x16x32_bf16 v[108:111], v[148:151], v[196:199], v[108:111]
	v_mfma_f32_16x16x32_bf16 v[104:107], v[156:159], v[196:199], v[104:107]
	v_mfma_f32_16x16x32_bf16 v[92:95], v[148:151], v[204:207], v[92:95]
	v_mfma_f32_16x16x32_bf16 v[88:91], v[156:159], v[204:207], v[88:91]
	v_mfma_f32_16x16x32_bf16 v[76:79], v[148:151], v[214:217], v[76:79]
	v_mfma_f32_16x16x32_bf16 v[72:75], v[156:159], v[214:217], v[72:75]
	v_mfma_f32_16x16x32_bf16 v[124:127], v[152:155], v[192:195], v[124:127]
	v_mfma_f32_16x16x32_bf16 v[120:123], v[160:163], v[192:195], v[120:123]
	v_mfma_f32_16x16x32_bf16 v[108:111], v[152:155], v[200:203], v[108:111]
	v_mfma_f32_16x16x32_bf16 v[104:107], v[160:163], v[200:203], v[104:107]
	v_mfma_f32_16x16x32_bf16 v[92:95], v[152:155], v[210:213], v[92:95]
	v_mfma_f32_16x16x32_bf16 v[88:91], v[160:163], v[210:213], v[88:91]
	v_mfma_f32_16x16x32_bf16 v[76:79], v[152:155], v[218:221], v[76:79]
	v_mfma_f32_16x16x32_bf16 v[72:75], v[160:163], v[218:221], v[72:75]
	s_setprio 0
	s_setprio 1
	v_mfma_f32_16x16x32_bf16 v[116:119], v[172:175], v[188:191], v[116:119]
	v_mfma_f32_16x16x32_bf16 v[112:115], v[180:183], v[188:191], v[112:115]
	v_mfma_f32_16x16x32_bf16 v[100:103], v[172:175], v[196:199], v[100:103]
	v_mfma_f32_16x16x32_bf16 v[96:99], v[180:183], v[196:199], v[96:99]
	v_mfma_f32_16x16x32_bf16 v[84:87], v[172:175], v[204:207], v[84:87]
	v_mfma_f32_16x16x32_bf16 v[80:83], v[180:183], v[204:207], v[80:83]
	v_mfma_f32_16x16x32_bf16 v[68:71], v[172:175], v[214:217], v[68:71]
	v_mfma_f32_16x16x32_bf16 v[64:67], v[180:183], v[214:217], v[64:67]
	v_mfma_f32_16x16x32_bf16 v[116:119], v[176:179], v[192:195], v[116:119]
	v_mfma_f32_16x16x32_bf16 v[112:115], v[184:187], v[192:195], v[112:115]
	v_mfma_f32_16x16x32_bf16 v[100:103], v[176:179], v[200:203], v[100:103]
	v_mfma_f32_16x16x32_bf16 v[96:99], v[184:187], v[200:203], v[96:99]
	v_mfma_f32_16x16x32_bf16 v[84:87], v[176:179], v[210:213], v[84:87]
	v_mfma_f32_16x16x32_bf16 v[80:83], v[184:187], v[210:213], v[80:83]
	v_mfma_f32_16x16x32_bf16 v[68:71], v[176:179], v[218:221], v[68:71]
	v_mfma_f32_16x16x32_bf16 v[64:67], v[184:187], v[218:221], v[64:67]
	s_setprio 0
	s_barrier
; #define PG8_LDA(dst, b, h) do { _Pragma("unroll") for (int m = 0; m < 4; ++m) _Pragma("unroll") for (int k = 0; k < 2; ++k) dst[m][k] = *(const PG8_LAS bf16x8*)(lds + PG8_SA(b, h) + aoff + m * 2048 + k * 1024); } while (0)
; template <class Epi, class Sched, bool ALIGN_EPI = false, bool SP2 = false>
; __device__ __forceinline__ void gemm_phase(PG8_LAS unsigned char* lds, const Gemm g, const Sched& S, const Epi& E) {
;     ...
;             PG8_LDB(B0, 1, 0); PG8_LDB(B1, 1, 1); PG8_SCHED; PG8_LDA(At, 1, 0); PG8_STAGE(PG8_SA(0, 1), a2 + hstep, voffA);
;             PG8_WAIT_V(8); PG8_WAIT_L(0); PG8_BAR; PG8_MMA(0, 0, At, B0); PG8_MMA(0, 1, At, B1); PG8_BAR; PG8_SCHED;
;             PG8_LDA(At, 1, 1); PG8_STAGE(PG8_SB(1, 0), b3, voffB); PG8_STAGE(PG8_SB(1, 1), b3 + hstep, voffB); PG8_STAGE(PG8_SA(1, 0), a3, voffA);
;             PG8_WAIT_V(8); PG8_WAIT_L(0); PG8_BAR; PG8_MMA(1, 0, At, B0); PG8_MMA(1, 1, At, B1); PG8_BAR; PG8_SCHED;
;             } else {
;             PG8_LDB(B0, 0, 0); PG8_SCHED; PG8_LDA(At, 0, 0); PG8_STAGE(PG8_SA(1, 1), a1 + hstep, voffA);
;             PG8_WAIT_L(8); PG8_BAR; PG8_WAIT_L(0); PG8_MMA(0, 0, At, B0); PG8_BAR; PG8_SCHED;
;             PG8_LDB(B1, 0, 1); PG8_STAGE(PG8_SB(0, 0), b2, voffB);
;             PG8_BAR; PG8_WAIT_L(0); PG8_MMA(0, 1, At, B1); PG8_BAR;
;             PG8_LDA(At, 0, 1); PG8_STAGE(PG8_SA(0, 0), a2, voffA);
;             PG8_BAR; PG8_WAIT_L(0); PG8_MMA(1, 0, At, B0); PG8_BAR; PG8_SCHED;
;             PG8_STAGE(PG8_SB(0, 1), b2 + hstep, voffB);
;             PG8_WAIT_V(6); PG8_BAR; PG8_MMA(1, 1, At, B1); PG8_BAR;
;             PG8_LDB(B0, 1, 0); PG8_SCHED; PG8_LDA(At, 1, 0); PG8_STAGE(PG8_SA(0, 1), a2 + hstep, voffA);
;             PG8_WAIT_L(8); PG8_BAR; PG8_WAIT_L(0); PG8_MMA(0, 0, At, B0); PG8_BAR; PG8_SCHED;
;             PG8_LDB(B1, 1, 1); PG8_STAGE(PG8_SB(1, 0), b3, voffB);
;             PG8_BAR; PG8_WAIT_L(0); PG8_MMA(0, 1, At, B1); PG8_BAR;
;             PG8_LDA(At, 1, 1); PG8_STAGE(PG8_SA(1, 0), a3, voffA);
;             PG8_BAR; PG8_WAIT_L(0); PG8_MMA(1, 0, At, B0); PG8_BAR; PG8_SCHED;
;             PG8_STAGE(PG8_SB(1, 1), b3 + hstep, voffB);
;             PG8_WAIT_V(6); PG8_BAR; PG8_MMA(1, 1, At, B1); PG8_BAR;
;             }
;         }
;         if constexpr (ALIGN_EPI) { if (wr == 0) PG8_BAR; }
;         if constexpr (!Epi::AFTER_DRAIN) { E(acc, cur, wr, wc, fr, fq); S.done(cur); }
	s_add_i32 s52, s78, s61
	v_lshl_add_u64 v[164:165], v[164:165], 0, s[34:35]
	s_mov_b32 m0, s52
	ds_read_b128 v[188:191], v169 offset:49152
	ds_read_b128 v[192:195], v169 offset:50176
	ds_read_b128 v[196:199], v169 offset:51200
	ds_read_b128 v[200:203], v169 offset:52224
	ds_read_b128 v[204:207], v169 offset:53248
	ds_read_b128 v[210:213], v169 offset:54272
	ds_read_b128 v[214:217], v169 offset:55296
	ds_read_b128 v[218:221], v169 offset:56320
	global_load_lds_dwordx4 v[164:165], off
	s_add_i32 m0, s52, 0x2000
	s_add_u32 s52, s72, 0x40080
	v_lshl_add_u64 v[164:165], v[222:223], 0, s[34:35]
	s_addc_u32 s53, s73, 0
	s_add_i32 s72, vcc_hi, s61
	global_load_lds_dwordx4 v[164:165], off
	v_lshl_add_u64 v[164:165], s[52:53], 0, v[130:131]
	s_mov_b32 m0, s72
	s_nop 0
	global_load_lds_dwordx4 v[164:165], off
	v_lshl_add_u64 v[164:165], s[52:53], 0, v[134:135]
	s_add_i32 m0, s72, 0x2000
	s_nop 0
	global_load_lds_dwordx4 v[164:165], off
	v_lshl_add_u64 v[164:165], v[224:225], 0, s[34:35]
	s_mov_b32 m0, s83
	s_nop 0
	global_load_lds_dwordx4 v[164:165], off
	v_lshl_add_u64 v[164:165], v[226:227], 0, s[34:35]
	s_mov_b32 m0, s84
	s_nop 0
	global_load_lds_dwordx4 v[164:165], off
	s_waitcnt vmcnt(8)
	s_waitcnt lgkmcnt(0)
	s_barrier
	s_setprio 1
	s_waitcnt lgkmcnt(0)
	v_mfma_f32_16x16x32_bf16 v[60:63], v[148:151], v[188:191], v[60:63]
	v_mfma_f32_16x16x32_bf16 v[56:59], v[156:159], v[188:191], v[56:59]
	v_mfma_f32_16x16x32_bf16 v[44:47], v[148:151], v[196:199], v[44:47]
	v_mfma_f32_16x16x32_bf16 v[40:43], v[156:159], v[196:199], v[40:43]
	v_mfma_f32_16x16x32_bf16 v[28:31], v[148:151], v[204:207], v[28:31]
	v_mfma_f32_16x16x32_bf16 v[24:27], v[156:159], v[204:207], v[24:27]
	v_mfma_f32_16x16x32_bf16 v[12:15], v[148:151], v[214:217], v[12:15]
	v_mfma_f32_16x16x32_bf16 v[8:11], v[156:159], v[214:217], v[8:11]
	v_mfma_f32_16x16x32_bf16 v[60:63], v[152:155], v[192:195], v[60:63]
	v_mfma_f32_16x16x32_bf16 v[56:59], v[160:163], v[192:195], v[56:59]
	v_mfma_f32_16x16x32_bf16 v[44:47], v[152:155], v[200:203], v[44:47]
	v_mfma_f32_16x16x32_bf16 v[40:43], v[160:163], v[200:203], v[40:43]
	v_mfma_f32_16x16x32_bf16 v[28:31], v[152:155], v[210:213], v[28:31]
	v_mfma_f32_16x16x32_bf16 v[24:27], v[160:163], v[210:213], v[24:27]
	v_mfma_f32_16x16x32_bf16 v[12:15], v[152:155], v[218:221], v[12:15]
	v_mfma_f32_16x16x32_bf16 v[8:11], v[160:163], v[218:221], v[8:11]
	s_setprio 0
	s_setprio 1
	v_mfma_f32_16x16x32_bf16 v[52:55], v[172:175], v[188:191], v[52:55]
	v_mfma_f32_16x16x32_bf16 v[48:51], v[180:183], v[188:191], v[48:51]
	v_mfma_f32_16x16x32_bf16 v[36:39], v[172:175], v[196:199], v[36:39]
	v_mfma_f32_16x16x32_bf16 v[32:35], v[180:183], v[196:199], v[32:35]
	v_mfma_f32_16x16x32_bf16 v[20:23], v[172:175], v[204:207], v[20:23]
	v_mfma_f32_16x16x32_bf16 v[16:19], v[180:183], v[204:207], v[16:19]
	v_mfma_f32_16x16x32_bf16 v[4:7], v[172:175], v[214:217], v[4:7]
	v_mfma_f32_16x16x32_bf16 v[0:3], v[180:183], v[214:217], v[0:3]
	v_mfma_f32_16x16x32_bf16 v[52:55], v[176:179], v[192:195], v[52:55]
	v_mfma_f32_16x16x32_bf16 v[48:51], v[184:187], v[192:195], v[48:51]
	v_mfma_f32_16x16x32_bf16 v[36:39], v[176:179], v[200:203], v[36:39]
	v_mfma_f32_16x16x32_bf16 v[32:35], v[184:187], v[200:203], v[32:35]
	v_mfma_f32_16x16x32_bf16 v[20:23], v[176:179], v[210:213], v[20:23]
	v_mfma_f32_16x16x32_bf16 v[16:19], v[184:187], v[210:213], v[16:19]
	v_mfma_f32_16x16x32_bf16 v[4:7], v[176:179], v[218:221], v[4:7]
	v_mfma_f32_16x16x32_bf16 v[0:3], v[184:187], v[218:221], v[0:3]
	s_setprio 0
	s_barrier
	s_add_i32 vcc_lo, vcc_lo, 2
	s_add_u32 s8, s8, 0x100
	s_addc_u32 s9, s9, 0
	s_add_u32 s96, s96, 0x100
	s_addc_u32 s97, s97, 0
	s_cmp_gt_u32 vcc_lo, 13
	s_cbranch_scc0 .LBB0_462
	s_cmp_eq_u32 s101, 0
	s_cbranch_scc1 .Lp3_war_ok
	s_mov_b64 exec, 1
	s_lshl_b32 s98, s33, 8
	s_add_u32 s98, s46, s98
	s_addc_u32 s99, s47, 0
	v_mov_b32_e32 v176, 0x10000
	s_mov_b32 s73, 0
.Lp3_war_poll:
	global_load_dword v177, v176, s[98:99] sc1
	s_waitcnt vmcnt(0)
	v_readfirstlane_b32 s72, v177
	s_cmp_ge_u32 s72, s101
	s_cbranch_scc1 .Lp3_war_done
	s_sleep 1
	s_add_i32 s73, s73, 1
	s_cmp_lt_u32 s73, 20000
	s_cbranch_scc1 .Lp3_war_poll
.Lp3_war_done:
	s_mov_b32 s101, 0
	s_mov_b64 exec, -1
.Lp3_war_ok:
	s_and_b64 vcc, exec, s[36:37]
	s_cbranch_vccnz .LBB0_467
	v_lshl_add_u32 v148, s6, 8, v139
	s_cmp_lt_i32 s14, 10
	s_mov_b64 s[6:7], -1
	s_cbranch_scc1 .LBB0_468

; __global__ void __launch_bounds__(NT, 2) hymba_fwd(Args args) {
	.amdhsa_kernel _Z9hymba_fwd4Args
		.amdhsa_group_segment_fixed_size 0
		.amdhsa_private_segment_fixed_size 0
		.amdhsa_kernarg_size 448
		.amdhsa_user_sgpr_count 2
		.amdhsa_user_sgpr_dispatch_ptr 0
		.amdhsa_user_sgpr_queue_ptr 0
		.amdhsa_user_sgpr_kernarg_segment_ptr 1
		.amdhsa_user_sgpr_dispatch_id 0
		.amdhsa_user_sgpr_kernarg_preload_length 0
		.amdhsa_user_sgpr_kernarg_preload_offset 0
		.amdhsa_user_sgpr_private_segment_size 0
		.amdhsa_uses_dynamic_stack 0
		.amdhsa_enable_private_segment 0
		.amdhsa_system_sgpr_workgroup_id_x 1
		.amdhsa_system_sgpr_workgroup_id_y 0
		.amdhsa_system_sgpr_workgroup_id_z 0
		.amdhsa_system_sgpr_workgroup_info 0
		.amdhsa_system_vgpr_workitem_id 2
		.amdhsa_next_free_vgpr 249
		.amdhsa_next_free_sgpr 102
		.amdhsa_accum_offset 252
		.amdhsa_reserve_vcc 1
		.amdhsa_float_round_mode_32 0
		.amdhsa_float_round_mode_16_64 0
		.amdhsa_float_denorm_mode_32 3
		.amdhsa_float_denorm_mode_16_64 3
		.amdhsa_dx10_clamp 1
		.amdhsa_ieee_mode 1
		.amdhsa_fp16_overflow 0
		.amdhsa_tg_split 0
		.amdhsa_exception_fp_ieee_invalid_op 0
		.amdhsa_exception_fp_denorm_src 0
		.amdhsa_exception_fp_ieee_div_zero 0
		.amdhsa_exception_fp_ieee_overflow 0
		.amdhsa_exception_fp_ieee_underflow 0
		.amdhsa_exception_fp_ieee_inexact 0
		.amdhsa_exception_int_div_zero 0
	.end_amdhsa_kernel

; __global__ void __launch_bounds__(NT, 2) hymba_fwd(Args args) {
amdhsa.kernels:
  - .agpr_count:     0
    .args:
      - .offset:         0
        .size:           192
        .value_kind:     by_value
      - .offset:         192
        .size:           4
        .value_kind:     hidden_block_count_x
      - .offset:         196
        .size:           4
        .value_kind:     hidden_block_count_y
      - .offset:         200
        .size:           4
        .value_kind:     hidden_block_count_z
      - .offset:         204
        .size:           2
        .value_kind:     hidden_group_size_x
      - .offset:         206
        .size:           2
        .value_kind:     hidden_group_size_y
      - .offset:         208
        .size:           2
        .value_kind:     hidden_group_size_z
      - .offset:         210
        .size:           2
        .value_kind:     hidden_remainder_x
      - .offset:         212
        .size:           2
        .value_kind:     hidden_remainder_y
      - .offset:         214
        .size:           2
        .value_kind:     hidden_remainder_z
      - .offset:         232
        .size:           8
        .value_kind:     hidden_global_offset_x
      - .offset:         240
        .size:           8
        .value_kind:     hidden_global_offset_y
      - .offset:         248
        .size:           8
        .value_kind:     hidden_global_offset_z
      - .offset:         256
        .size:           2
        .value_kind:     hidden_grid_dims
      - .offset:         280
        .size:           8
        .value_kind:     hidden_multigrid_sync_arg
      - .offset:         312
        .size:           4
        .value_kind:     hidden_dynamic_lds_size
    .group_segment_fixed_size: 0
    .kernarg_segment_align: 8
    .kernarg_segment_size: 448
    .language:       OpenCL C
    .language_version:
      - 2
      - 0
    .max_flat_workgroup_size: 512
    .name:           _Z9hymba_fwd4Args
    .private_segment_fixed_size: 0
    .sgpr_count:     108
    .sgpr_spill_count: 7
    .symbol:         _Z9hymba_fwd4Args.kd
    .uniform_work_group_size: 1
    .uses_dynamic_stack: false
    .vgpr_count:     249
    .vgpr_spill_count: 0
    .wavefront_size: 64
